# s22 + odd-tile V ds_writes issued after the next QK's first four K-fragment reads (reads no longer queue behind the 13-cycle b128 stores)
# speedup vs baseline: 1.0006x; 1.0006x over previous
; #define SBAR() __builtin_amdgcn_sched_barrier(0)
; #define SLOAD(i, k0) do { sr_[i].vs0 = St::ld8(&Vh[(long)((k0) + sr) * LDK + sc]); sr_[i].vs1 = St::ld8(&Vh[(long)((k0) + 32 + sr) * LDK + sc]); \
;     sr_[i].ks0 = St::ld8(&Kh[(long)((k0) + sr) * LDK + sc]); sr_[i].ks1 = St::ld8(&Kh[(long)((k0) + 32 + sr) * LDK + sc]); } while (0)
; __device__ __forceinline__ void finishSM(f32x16& p0, f32x16& p1, float alpha, float& l_reg, bf16x8& pa0, bf16x8& pa1, bf16x8& pa2, bf16x8& pa3) {
;   for (int r = 0; r < 16; ++r) p1[r] = __builtin_amdgcn_exp2f(p1[r]);
;   float ps = 0; for (int r = 0; r < 16; ++r) ps += p0[r]; for (int r = 0; r < 16; ++r) ps += p1[r];
;   { auto rr = __builtin_amdgcn_permlane32_swap(__float_as_uint(ps), __float_as_uint(ps), false, false);
;     ps = __uint_as_float(rr[0]) + __uint_as_float(rr[1]); }
;   l_reg = l_reg * alpha + ps;
;     ...
;   PK4(p0, 0, pa0); PK4(p0, 8, pa1); PK4(p1, 0, pa2); PK4(p1, 8, pa3);
;     ...
; }
; __device__ __forceinline__ void qkt(f32x16& p0, f32x16& p1, const bf16* Ks, const bf16x8* qr, int r32, int hi) {
;   p0 = f32x16{}; p1 = f32x16{};
;   for (int d0 = 0; d0 < 8; ++d0) { int cb = (d0 * 16 + hi * 8) * 2;
;     bf16x8 b0 = *reinterpret_cast<const bf16x8*>((const char*)Ks + KSWZ(r32, cb));
;     bf16x8 b1 = *reinterpret_cast<const bf16x8*>((const char*)Ks + KSWZ(32 + r32, cb));
;     p0 = __builtin_amdgcn_mfma_f32_32x32x16_bf16(b0, qr[d0], p0, 0, 0, 0);
;     p1 = __builtin_amdgcn_mfma_f32_32x32x16_bf16(b1, qr[d0], p1, 0, 0, 0); }
; }
; __device__ __forceinline__ void attn_dense_body(const bf16* __restrict__ Qb, const bf16* __restrict__ Kh, const bf16* __restrict__ Vh,
;                                                 const unsigned short* __restrict__ Gb, unsigned short* __restrict__ Yb, int seq, char* lds, const int tid) {
;     ...
;     SBAR(); qkt(pB0, pB1, (bf16*)((char*)K_lds + SHM_K), qr, r32, hi);
;     finishSM(pA0, pA1, alA, l_reg, pa0, pa1, pa2, pa3); SBAR();
;     SLOAD(SO, (j + SDEPTH) * KVBLK); SBAR();
.LBB0_602:
	s_lshl_b32 s8, s65, 5
	v_add_co_u32_e32 v232, vcc, v251, v182
	s_add_i32 m0, s8, 0x8000
	s_nop 0
	v_addc_co_u32_e32 v233, vcc, -1, v183, vcc
	global_load_lds_dwordx4 v[232:233], off
	v_add_co_u32_e32 v232, vcc, v255, v182
	s_add_i32 m0, s8, 0x8400
	s_nop 0
	v_addc_co_u32_e32 v233, vcc, -1, v183, vcc
	global_load_lds_dwordx4 v[232:233], off
	ds_read_b128 v[64:67], v192 offset:49152
	ds_read_b128 v[68:71], v192 offset:57344
	ds_read_b128 v[242:245], v201 offset:49152
	ds_read_b128 v[246:249], v201 offset:57344
	v_exp_f32_e32 v160, v162
	v_add_f32_e32 v162, 0, v223
	s_waitcnt lgkmcnt(3)
	v_mfma_f32_32x32x16_bf16 v[80:95], v[64:67], v[126:129], 0
	v_add_f32_e32 v162, v224, v162
	v_add_f32_e32 v162, v225, v162
	v_add_f32_e32 v162, v227, v162
	v_add_f32_e32 v162, v229, v162
	v_add_f32_e32 v162, v230, v162
	v_add_f32_e32 v162, v226, v162
	v_add_f32_e32 v162, v228, v162
	s_waitcnt lgkmcnt(2)
	v_mfma_f32_32x32x16_bf16 v[64:79], v[68:71], v[126:129], 0
	v_add_f32_e32 v162, v215, v162
	v_add_f32_e32 v162, v217, v162
	v_add_f32_e32 v162, v219, v162
	v_add_f32_e32 v162, v221, v162
	v_add_f32_e32 v162, v216, v162
	v_add_f32_e32 v162, v218, v162
	v_add_f32_e32 v162, v220, v162
	s_waitcnt lgkmcnt(1)
	v_mfma_f32_32x32x16_bf16 v[80:95], v[242:245], v[122:125], v[80:95]
	v_add_f32_e32 v162, v222, v162
	v_exp_f32_e32 v154, v164
	v_exp_f32_e32 v155, v165
	v_exp_f32_e32 v156, v172
	v_exp_f32_e32 v157, v173
	v_exp_f32_e32 v158, v168
	v_exp_f32_e32 v159, v169
	s_waitcnt lgkmcnt(0)
	v_mfma_f32_32x32x16_bf16 v[64:79], v[246:249], v[122:125], v[64:79]
	ds_read_b128 v[242:245], v200 offset:49152
	ds_read_b128 v[246:249], v200 offset:57344
	v_exp_f32_e32 v161, v163
	v_cvt_pk_bf16_f32 v164, v229, v230
	v_cvt_pk_bf16_f32 v163, v225, v227
	v_cvt_pk_bf16_f32 v165, v226, v228
	v_cvt_pk_bf16_f32 v168, v216, v218
	v_cvt_pk_bf16_f32 v169, v220, v222
	s_waitcnt lgkmcnt(1)
	v_mfma_f32_32x32x16_bf16 v[80:95], v[242:245], v[134:137], v[80:95]
	v_exp_f32_e32 v146, v176
	v_exp_f32_e32 v147, v177
	v_exp_f32_e32 v148, v174
	v_exp_f32_e32 v149, v175
	v_permlane32_swap_b32_e32 v163, v165
	s_waitcnt lgkmcnt(0)
	v_mfma_f32_32x32x16_bf16 v[64:79], v[246:249], v[134:137], v[64:79]
	ds_read_b128 v[242:245], v195 offset:49152
	ds_read_b128 v[246:249], v195 offset:57344
	v_add_f32_e32 v162, v146, v162
	v_add_f32_e32 v162, v147, v162
	v_add_f32_e32 v162, v148, v162
	v_exp_f32_e32 v150, v170
	s_waitcnt lgkmcnt(1)
	v_mfma_f32_32x32x16_bf16 v[80:95], v[242:245], v[130:133], v[80:95]
	v_exp_f32_e32 v151, v171
	v_exp_f32_e32 v152, v166
	v_exp_f32_e32 v153, v167
	v_add_f32_e32 v162, v149, v162
	s_waitcnt lgkmcnt(0)
	v_mfma_f32_32x32x16_bf16 v[64:79], v[246:249], v[130:133], v[64:79]
	ds_read_b128 v[242:245], v194 offset:49152
	ds_read_b128 v[246:249], v194 offset:57344
	v_add_f32_e32 v162, v150, v162
	v_add_f32_e32 v162, v151, v162
	v_add_f32_e32 v162, v152, v162
	v_add_f32_e32 v162, v153, v162
	s_waitcnt lgkmcnt(1)
	v_mfma_f32_32x32x16_bf16 v[80:95], v[242:245], v[118:121], v[80:95]
	v_add_f32_e32 v162, v154, v162
	v_add_f32_e32 v162, v155, v162
	v_add_f32_e32 v162, v156, v162
	v_add_f32_e32 v162, v157, v162
	s_waitcnt lgkmcnt(0)
	v_mfma_f32_32x32x16_bf16 v[64:79], v[246:249], v[118:121], v[64:79]
	ds_read_b128 v[242:245], v193 offset:49152
	ds_read_b128 v[246:249], v193 offset:57344
	v_add_f32_e32 v162, v158, v162
	v_add_f32_e32 v162, v159, v162
	v_add_f32_e32 v162, v160, v162
	v_add_f32_e32 v211, v161, v162
	s_waitcnt lgkmcnt(1)
	v_mfma_f32_32x32x16_bf16 v[80:95], v[242:245], v[114:117], v[80:95]
	v_mov_b32_e32 v212, v211
	v_cvt_pk_bf16_f32 v162, v223, v224
	s_nop 0
	v_permlane32_swap_b32_e32 v211, v212
	s_waitcnt lgkmcnt(0)
	v_mfma_f32_32x32x16_bf16 v[64:79], v[246:249], v[114:117], v[64:79]
	ds_read_b128 v[242:245], v207 offset:49152
	ds_read_b128 v[246:249], v207 offset:57344
	v_permlane32_swap_b32_e32 v162, v164
	v_cvt_pk_bf16_f32 v166, v215, v217
	v_cvt_pk_bf16_f32 v167, v219, v221
	v_cvt_pk_bf16_f32 v170, v146, v147
	s_waitcnt lgkmcnt(1)
	v_mfma_f32_32x32x16_bf16 v[80:95], v[242:245], v[110:113], v[80:95]
	v_cvt_pk_bf16_f32 v171, v148, v149
	v_cvt_pk_bf16_f32 v172, v150, v151
	v_cvt_pk_bf16_f32 v173, v152, v153
	v_cvt_pk_bf16_f32 v174, v154, v155
	s_waitcnt lgkmcnt(0)
	v_mfma_f32_32x32x16_bf16 v[64:79], v[246:249], v[110:113], v[64:79]
	ds_read_b128 v[242:245], v206 offset:49152
	ds_read_b128 v[246:249], v206 offset:57344
	v_cvt_pk_bf16_f32 v175, v156, v157
	v_cvt_pk_bf16_f32 v176, v158, v159
	v_cvt_pk_bf16_f32 v177, v160, v161
	s_waitcnt lgkmcnt(1)
	v_mfma_f32_32x32x16_bf16 v[80:95], v[242:245], v[106:109], v[80:95]
	v_permlane32_swap_b32_e32 v166, v168
	v_permlane32_swap_b32_e32 v167, v169
	v_permlane32_swap_b32_e32 v170, v172
	s_waitcnt lgkmcnt(0)
	v_mfma_f32_32x32x16_bf16 v[64:79], v[246:249], v[106:109], v[64:79]
	v_permlane32_swap_b32_e32 v171, v173
	v_permlane32_swap_b32_e32 v174, v176
	v_permlane32_swap_b32_e32 v175, v177
	v_add_co_u32_e32 v146, vcc, s69, v182
	s_mov_b32 s8, 0xffff0000
	s_nop 0
	v_addc_co_u32_e32 v147, vcc, -1, v183, vcc
	v_add_co_u32_e32 v150, vcc, s8, v182
	s_nop 1
	v_addc_co_u32_e32 v151, vcc, -1, v183, vcc
	global_load_dwordx4 v[146:149], v[146:147], off
	s_nop 0
	global_load_dwordx4 v[150:153], v[150:151], off
	ds_read_b64_tr_b16 v[214:215], v179 offset:0
	ds_read_b64_tr_b16 v[216:217], v179 offset:0x800
	ds_read_b64_tr_b16 v[218:219], v179 offset:0x1000
	ds_read_b64_tr_b16 v[220:221], v179 offset:0x1800
	ds_read_b64_tr_b16 v[222:223], v179 offset:0x2000
	ds_read_b64_tr_b16 v[224:225], v179 offset:0x2800
	ds_read_b64_tr_b16 v[226:227], v179 offset:0x3000
	ds_read_b64_tr_b16 v[228:229], v179 offset:0x3800
	s_waitcnt lgkmcnt(0)
; #define SBAR() __builtin_amdgcn_sched_barrier(0)
; __device__ __forceinline__ void partialSM(f32x16& p0, f32x16& p1, float& m_reg, float& mn, float& alpha) {
;   constexpr float C = SCALE * 1.4426950408889634f;
;   float pmax = p0[0]; for (int r = 1; r < 16; ++r) pmax = fmaxf(pmax, p0[r]); for (int r = 0; r < 16; ++r) pmax = fmaxf(pmax, p1[r]);
;   { auto rr = __builtin_amdgcn_permlane32_swap(__float_as_uint(pmax), __float_as_uint(pmax), false, false);
;     pmax = fmaxf(__uint_as_float(rr[0]), __uint_as_float(rr[1])); }
;   if (__builtin_expect(__all(pmax - m_reg <= THR / SCALE), 1)) { mn = m_reg; alpha = 1.f; }
;   else { mn = fmaxf(m_reg, pmax); alpha = __builtin_amdgcn_exp2f((m_reg - mn) * C); m_reg = mn; }
;   float mnC = -mn * C;
;   for (int r = 0; r < 16; ++r) p0[r] = fmaf(p0[r], C, mnC); for (int r = 0; r < 16; ++r) p1[r] = fmaf(p1[r], C, mnC);
;   for (int r = 0; r < 16; ++r) p0[r] = __builtin_amdgcn_exp2f(p0[r]);
; }
; template <int D0> __device__ __forceinline__ void pv_one(f32x16& od, int vb, bf16x8 pa0, bf16x8 pa1, bf16x8 pa2, bf16x8 pa3) {
;   const s16x4 l0 = tr_read<v_rd_off(D0, 0, 0)>(vb), h0 = tr_read<v_rd_off(D0, 0, 1)>(vb), l1 = tr_read<v_rd_off(D0, 1, 0)>(vb), h1 = tr_read<v_rd_off(D0, 1, 1)>(vb);
;   const s16x4 l2 = tr_read<v_rd_off(D0, 2, 0)>(vb), h2 = tr_read<v_rd_off(D0, 2, 1)>(vb), l3 = tr_read<v_rd_off(D0, 3, 0)>(vb), h3 = tr_read<v_rd_off(D0, 3, 1)>(vb);
;   asm volatile("s_waitcnt lgkmcnt(0)" ::: "memory"); SBAR();
;     ...
;   od = __builtin_amdgcn_mfma_f32_32x32x16_bf16(pa0, PK(l0, h0), od, 0, 0, 0);
;   od = __builtin_amdgcn_mfma_f32_32x32x16_bf16(pa1, PK(l1, h1), od, 0, 0, 0);
;   od = __builtin_amdgcn_mfma_f32_32x32x16_bf16(pa2, PK(l2, h2), od, 0, 0, 0);
;   od = __builtin_amdgcn_mfma_f32_32x32x16_bf16(pa3, PK(l3, h3), od, 0, 0, 0);
;     ...
; }
; __device__ __forceinline__ void pv_d0(f32x16* o, int vb, bf16x8 pa0, bf16x8 pa1, bf16x8 pa2, bf16x8 pa3) {
;   pv_one<0>(o[0], vb, pa0, pa1, pa2, pa3); pv_one<1>(o[1], vb, pa0, pa1, pa2, pa3); pv_one<2>(o[2], vb, pa0, pa1, pa2, pa3); pv_one<3>(o[3], vb, pa0, pa1, pa2, pa3);
	s_nop 0
	v_mfma_f32_32x32x16_bf16 v[0:15], v[162:165], v[214:217], v[0:15]
	ds_read_b64_tr_b16 v[214:215], v179 offset:0x200
	ds_read_b64_tr_b16 v[216:217], v179 offset:0xa00
	v_max_f32_e32 v232, v81, v81
	v_max_f32_e32 v233, v80, v80
	v_max_f32_e32 v232, v233, v232
	v_max3_f32 v232, v232, v82, v83
	v_max3_f32 v232, v232, v84, v85
	v_max3_f32 v232, v232, v86, v87
	v_mfma_f32_32x32x16_bf16 v[0:15], v[166:169], v[218:221], v[0:15]
	ds_read_b64_tr_b16 v[218:219], v179 offset:0x1200
	ds_read_b64_tr_b16 v[220:221], v179 offset:0x1a00
	v_max3_f32 v232, v232, v88, v89
	v_max3_f32 v232, v232, v90, v91
	v_max3_f32 v232, v232, v92, v93
	v_max3_f32 v232, v232, v94, v95
	v_max3_f32 v232, v232, v64, v65
	v_max3_f32 v232, v232, v66, v67
	v_mfma_f32_32x32x16_bf16 v[0:15], v[170:173], v[222:225], v[0:15]
	ds_read_b64_tr_b16 v[222:223], v179 offset:0x2200
	ds_read_b64_tr_b16 v[224:225], v179 offset:0x2a00
	v_max3_f32 v232, v232, v68, v69
	v_max3_f32 v232, v232, v70, v71
	v_max3_f32 v232, v232, v72, v73
	v_max3_f32 v232, v232, v74, v75
	v_max3_f32 v232, v232, v76, v77
	v_max3_f32 v232, v232, v78, v79
	v_mfma_f32_32x32x16_bf16 v[0:15], v[174:177], v[226:229], v[0:15]
	ds_read_b64_tr_b16 v[226:227], v179 offset:0x3200
	ds_read_b64_tr_b16 v[228:229], v179 offset:0x3a00
	v_mov_b32_e32 v233, v232
	s_nop 1
	v_permlane32_swap_b32_e32 v232, v233
	v_max_f32_e32 v233, v233, v233
	v_max_f32_e32 v232, v232, v232
	v_max_f32_e32 v232, v232, v233
	s_waitcnt lgkmcnt(0)
	v_mfma_f32_32x32x16_bf16 v[48:63], v[162:165], v[214:217], v[48:63]
	ds_read_b64_tr_b16 v[214:215], v179 offset:0x400
	ds_read_b64_tr_b16 v[216:217], v179 offset:0xc00
	v_sub_f32_e32 v233, v232, v210
	v_cmp_ge_f32_e32 vcc, s68, v233
	v_max_f32_e32 v233, v210, v210
	v_max_f32_e32 v232, v233, v232
	v_sub_f32_e32 v233, v210, v232
	v_mul_f32_e32 v233, 0x3e0293ee, v233
	v_mfma_f32_32x32x16_bf16 v[48:63], v[166:169], v[218:221], v[48:63]
	ds_read_b64_tr_b16 v[218:219], v179 offset:0x1400
	ds_read_b64_tr_b16 v[220:221], v179 offset:0x1c00
	s_cmp_eq_u64 vcc, exec
	s_cselect_b64 s[8:9], -1, 0
	v_exp_f32_e32 v233, v233
	v_mfma_f32_32x32x16_bf16 v[48:63], v[170:173], v[222:225], v[48:63]
	ds_read_b64_tr_b16 v[222:223], v179 offset:0x2400
	ds_read_b64_tr_b16 v[224:225], v179 offset:0x2c00
	v_cndmask_b32_e64 v210, v232, v210, s[8:9]
	v_mul_f32_e32 v213, 0xbe0293ee, v210
	v_fmamk_f32 v80, v80, 0x3e0293ee, v213
	v_fmamk_f32 v81, v81, 0x3e0293ee, v213
	v_fmamk_f32 v82, v82, 0x3e0293ee, v213
	v_fmamk_f32 v83, v83, 0x3e0293ee, v213
	v_mfma_f32_32x32x16_bf16 v[48:63], v[174:177], v[226:229], v[48:63]
	ds_read_b64_tr_b16 v[226:227], v179 offset:0x3400
	ds_read_b64_tr_b16 v[228:229], v179 offset:0x3c00
	v_fmamk_f32 v84, v84, 0x3e0293ee, v213
	v_fmamk_f32 v85, v85, 0x3e0293ee, v213
	v_fmamk_f32 v86, v86, 0x3e0293ee, v213
	v_fmamk_f32 v87, v87, 0x3e0293ee, v213
	v_fmamk_f32 v88, v88, 0x3e0293ee, v213
	v_fmamk_f32 v89, v89, 0x3e0293ee, v213
	s_waitcnt lgkmcnt(0)
	v_mfma_f32_32x32x16_bf16 v[32:47], v[162:165], v[214:217], v[32:47]
	ds_read_b64_tr_b16 v[214:215], v179 offset:0x600
	ds_read_b64_tr_b16 v[216:217], v179 offset:0xe00
	v_fmamk_f32 v90, v90, 0x3e0293ee, v213
	v_fmamk_f32 v91, v91, 0x3e0293ee, v213
	v_fmamk_f32 v92, v92, 0x3e0293ee, v213
	v_fmamk_f32 v93, v93, 0x3e0293ee, v213
	v_fmamk_f32 v94, v94, 0x3e0293ee, v213
	v_fmamk_f32 v95, v95, 0x3e0293ee, v213
	v_mfma_f32_32x32x16_bf16 v[32:47], v[166:169], v[218:221], v[32:47]
	ds_read_b64_tr_b16 v[218:219], v179 offset:0x1600
	ds_read_b64_tr_b16 v[220:221], v179 offset:0x1e00
	v_exp_f32_e32 v80, v80
	v_exp_f32_e32 v81, v81
	v_exp_f32_e32 v82, v82
	v_mfma_f32_32x32x16_bf16 v[32:47], v[170:173], v[222:225], v[32:47]
	ds_read_b64_tr_b16 v[222:223], v179 offset:0x2600
	ds_read_b64_tr_b16 v[224:225], v179 offset:0x2e00
	v_exp_f32_e32 v83, v83
	v_exp_f32_e32 v84, v84
	v_exp_f32_e32 v85, v85
	v_mfma_f32_32x32x16_bf16 v[32:47], v[174:177], v[226:229], v[32:47]
	ds_read_b64_tr_b16 v[226:227], v179 offset:0x3600
	ds_read_b64_tr_b16 v[228:229], v179 offset:0x3e00
	v_exp_f32_e32 v86, v86
	v_exp_f32_e32 v87, v87
	v_exp_f32_e32 v88, v88
	s_waitcnt lgkmcnt(0)
	v_mfma_f32_32x32x16_bf16 v[16:31], v[162:165], v[214:217], v[16:31]
	v_exp_f32_e32 v89, v89
	v_exp_f32_e32 v90, v90
	v_exp_f32_e32 v91, v91
	v_mfma_f32_32x32x16_bf16 v[16:31], v[166:169], v[218:221], v[16:31]
	v_exp_f32_e32 v92, v92
	v_exp_f32_e32 v93, v93
	v_mfma_f32_32x32x16_bf16 v[16:31], v[170:173], v[222:225], v[16:31]
	v_exp_f32_e32 v94, v94
	v_exp_f32_e32 v95, v95
	v_mfma_f32_32x32x16_bf16 v[16:31], v[174:177], v[226:229], v[16:31]
	s_waitcnt vmcnt(2)
	s_barrier
	s_waitcnt vmcnt(4)
	v_cndmask_b32_e64 v214, v233, 1.0, s[8:9]
	v_cmp_gt_f32_e32 vcc, 1.0, v214
	s_cbranch_vccz .LBB0_606
	s_and_saveexec_b64 s[12:13], s[6:7]
	ds_write_b32 v189, v214 offset:128
	s_or_b64 exec, exec, s[12:13]
	s_waitcnt lgkmcnt(0)
	v_add_u32_e32 v163, v181, v180
	ds_read_b128 v[164:167], v163 offset:224
	ds_read_b128 v[168:171], v163 offset:192
	ds_read_b128 v[172:175], v163 offset:160
	ds_read_b128 v[216:219], v163 offset:128
	s_waitcnt lgkmcnt(3)
	v_pk_mul_f32 v[12:13], v[12:13], v[164:165]
	s_waitcnt lgkmcnt(2)
	v_pk_mul_f32 v[8:9], v[8:9], v[168:169]
	s_waitcnt lgkmcnt(1)
	v_pk_mul_f32 v[4:5], v[4:5], v[172:173]
	v_pk_mul_f32 v[14:15], v[14:15], v[166:167]
	v_pk_mul_f32 v[10:11], v[10:11], v[170:171]
	v_pk_mul_f32 v[6:7], v[6:7], v[174:175]
	s_waitcnt lgkmcnt(0)
	v_pk_mul_f32 v[2:3], v[2:3], v[218:219]
	v_pk_mul_f32 v[0:1], v[0:1], v[216:217]
	v_pk_mul_f32 v[60:61], v[60:61], v[164:165]
	v_pk_mul_f32 v[56:57], v[56:57], v[168:169]
	v_pk_mul_f32 v[52:53], v[52:53], v[172:173]
	v_pk_mul_f32 v[62:63], v[62:63], v[166:167]
	v_pk_mul_f32 v[58:59], v[58:59], v[170:171]
	v_pk_mul_f32 v[54:55], v[54:55], v[174:175]
	v_pk_mul_f32 v[50:51], v[50:51], v[218:219]
	v_pk_mul_f32 v[48:49], v[48:49], v[216:217]
	v_pk_mul_f32 v[44:45], v[44:45], v[164:165]
	v_pk_mul_f32 v[40:41], v[40:41], v[168:169]
	v_pk_mul_f32 v[36:37], v[36:37], v[172:173]
	v_pk_mul_f32 v[46:47], v[46:47], v[166:167]
	v_pk_mul_f32 v[42:43], v[42:43], v[170:171]
	v_pk_mul_f32 v[38:39], v[38:39], v[174:175]
	v_pk_mul_f32 v[34:35], v[34:35], v[218:219]
	v_pk_mul_f32 v[32:33], v[32:33], v[216:217]
	v_pk_mul_f32 v[28:29], v[28:29], v[164:165]
	v_pk_mul_f32 v[24:25], v[24:25], v[168:169]
	v_pk_mul_f32 v[20:21], v[20:21], v[172:173]
	v_pk_mul_f32 v[30:31], v[30:31], v[166:167]
	v_pk_mul_f32 v[26:27], v[26:27], v[170:171]
	v_pk_mul_f32 v[22:23], v[22:23], v[174:175]
	v_pk_mul_f32 v[18:19], v[18:19], v[218:219]
	v_pk_mul_f32 v[16:17], v[16:17], v[216:217]
; __device__ __forceinline__ void partialSM(f32x16& p0, f32x16& p1, float& m_reg, float& mn, float& alpha) {
;     ...
;   float mnC = -mn * C;
;   for (int r = 0; r < 16; ++r) p0[r] = fmaf(p0[r], C, mnC); for (int r = 0; r < 16; ++r) p1[r] = fmaf(p1[r], C, mnC);
;   for (int r = 0; r < 16; ++r) p0[r] = __builtin_amdgcn_exp2f(p0[r]);
; }
; __device__ __forceinline__ void finishSM(f32x16& p0, f32x16& p1, float alpha, float& l_reg, bf16x8& pa0, bf16x8& pa1, bf16x8& pa2, bf16x8& pa3) {
;   for (int r = 0; r < 16; ++r) p1[r] = __builtin_amdgcn_exp2f(p1[r]);
;   float ps = 0; for (int r = 0; r < 16; ++r) ps += p0[r]; for (int r = 0; r < 16; ++r) ps += p1[r];
;   { auto rr = __builtin_amdgcn_permlane32_swap(__float_as_uint(ps), __float_as_uint(ps), false, false);
;     ps = __uint_as_float(rr[0]) + __uint_as_float(rr[1]); }
;   l_reg = l_reg * alpha + ps;
;     ...
;   PK4(p0, 0, pa0); PK4(p0, 8, pa1); PK4(p1, 0, pa2); PK4(p1, 8, pa3);
;     ...
; }
; __device__ __forceinline__ void qkt(f32x16& p0, f32x16& p1, const bf16* Ks, const bf16x8* qr, int r32, int hi) {
;   p0 = f32x16{}; p1 = f32x16{};
;   for (int d0 = 0; d0 < 8; ++d0) { int cb = (d0 * 16 + hi * 8) * 2;
;     bf16x8 b0 = *reinterpret_cast<const bf16x8*>((const char*)Ks + KSWZ(r32, cb));
;     bf16x8 b1 = *reinterpret_cast<const bf16x8*>((const char*)Ks + KSWZ(32 + r32, cb));
;     p0 = __builtin_amdgcn_mfma_f32_32x32x16_bf16(b0, qr[d0], p0, 0, 0, 0);
;     p1 = __builtin_amdgcn_mfma_f32_32x32x16_bf16(b1, qr[d0], p1, 0, 0, 0); }
; }
.LBB0_606:
	s_lshl_b32 s8, s65, 5
	v_add_u32_e32 v232, 0x10000, v251
	s_add_i32 m0, s8, 0xc000
	v_add_co_u32_e32 v232, vcc, v232, v182
	s_nop 1
	v_addc_co_u32_e32 v233, vcc, -1, v183, vcc
	global_load_lds_dwordx4 v[232:233], off
	v_add_u32_e32 v232, 0x10000, v255
	s_add_i32 m0, s8, 0xc400
	v_add_co_u32_e32 v232, vcc, v232, v182
	s_nop 1
	v_addc_co_u32_e32 v233, vcc, -1, v183, vcc
	global_load_lds_dwordx4 v[232:233], off
	v_mov_b32_e32 v162, v80
	v_mov_b32_e32 v163, v81
	v_mov_b32_e32 v164, v82
	v_mov_b32_e32 v175, v83
	v_mov_b32_e32 v176, v84
	v_mov_b32_e32 v177, v85
	v_mov_b32_e32 v165, v86
	v_mov_b32_e32 v174, v87
	v_mov_b32_e32 v166, v88
	v_mov_b32_e32 v167, v89
	v_mov_b32_e32 v172, v90
	v_mov_b32_e32 v173, v91
	v_mov_b32_e32 v168, v92
	v_mov_b32_e32 v169, v93
	v_mov_b32_e32 v170, v94
	v_mov_b32_e32 v171, v95
	v_fmamk_f32 v223, v64, 0x3e0293ee, v213
	v_fmamk_f32 v224, v65, 0x3e0293ee, v213
	v_fmamk_f32 v225, v66, 0x3e0293ee, v213
	v_fmamk_f32 v226, v67, 0x3e0293ee, v213
	v_fmamk_f32 v227, v68, 0x3e0293ee, v213
	v_fmamk_f32 v216, v69, 0x3e0293ee, v213
	v_fmamk_f32 v217, v70, 0x3e0293ee, v213
	v_fmamk_f32 v218, v71, 0x3e0293ee, v213
	v_fmamk_f32 v219, v72, 0x3e0293ee, v213
	v_fmamk_f32 v220, v73, 0x3e0293ee, v213
	v_fmamk_f32 v221, v74, 0x3e0293ee, v213
	v_fmamk_f32 v222, v75, 0x3e0293ee, v213
	v_fmamk_f32 v215, v76, 0x3e0293ee, v213
	v_fmamk_f32 v228, v77, 0x3e0293ee, v213
	v_fmamk_f32 v229, v78, 0x3e0293ee, v213
	v_fmac_f32_e32 v213, 0x3e0293ee, v79
	ds_read_b128 v[64:67], v192 offset:32768
	ds_read_b128 v[68:71], v192 offset:40960
	ds_read_b128 v[242:245], v201 offset:32768
	ds_read_b128 v[246:249], v201 offset:40960
	ds_write_b128 v204, v[98:101]
	ds_write_b128 v205, v[138:141]
	v_add_f32_e32 v230, 0, v162
	v_add_f32_e32 v230, v163, v230
	s_waitcnt lgkmcnt(5)
	v_mfma_f32_32x32x16_bf16 v[80:95], v[64:67], v[126:129], 0
	v_add_f32_e32 v230, v164, v230
	v_add_f32_e32 v230, v175, v230
	v_add_f32_e32 v230, v176, v230
	v_add_f32_e32 v230, v177, v230
	v_add_f32_e32 v230, v165, v230
	v_add_f32_e32 v230, v174, v230
	v_add_f32_e32 v230, v166, v230
	s_waitcnt lgkmcnt(4)
	v_mfma_f32_32x32x16_bf16 v[64:79], v[68:71], v[126:129], 0
	v_add_f32_e32 v230, v167, v230
	v_add_f32_e32 v230, v172, v230
	v_add_f32_e32 v230, v173, v230
	v_exp_f32_e32 v223, v223
	v_add_f32_e32 v230, v168, v230
	v_exp_f32_e32 v224, v224
	v_add_f32_e32 v230, v169, v230
	s_waitcnt lgkmcnt(3)
	v_mfma_f32_32x32x16_bf16 v[80:95], v[242:245], v[122:125], v[80:95]
	v_exp_f32_e32 v225, v225
	v_add_f32_e32 v230, v170, v230
	v_exp_f32_e32 v226, v226
	v_add_f32_e32 v230, v171, v230
	v_exp_f32_e32 v227, v227
	v_add_f32_e32 v230, v223, v230
	v_exp_f32_e32 v216, v216
	s_waitcnt lgkmcnt(2)
	v_mfma_f32_32x32x16_bf16 v[64:79], v[246:249], v[122:125], v[64:79]
	ds_read_b128 v[242:245], v200 offset:32768
	ds_read_b128 v[246:249], v200 offset:40960
	v_add_f32_e32 v230, v224, v230
	v_exp_f32_e32 v217, v217
	v_add_f32_e32 v230, v225, v230
	v_exp_f32_e32 v218, v218
	v_add_f32_e32 v230, v226, v230
	v_exp_f32_e32 v219, v219
	s_waitcnt lgkmcnt(1)
	v_mfma_f32_32x32x16_bf16 v[80:95], v[242:245], v[134:137], v[80:95]
	v_add_f32_e32 v230, v227, v230
	v_exp_f32_e32 v220, v220
	v_add_f32_e32 v230, v216, v230
	v_exp_f32_e32 v221, v221
	v_add_f32_e32 v230, v217, v230
	v_exp_f32_e32 v222, v222
	v_add_f32_e32 v230, v218, v230
	s_waitcnt lgkmcnt(0)
	v_mfma_f32_32x32x16_bf16 v[64:79], v[246:249], v[134:137], v[64:79]
	ds_read_b128 v[242:245], v195 offset:32768
	ds_read_b128 v[246:249], v195 offset:40960
	v_exp_f32_e32 v215, v215
	v_add_f32_e32 v230, v219, v230
	v_exp_f32_e32 v228, v228
	v_add_f32_e32 v230, v220, v230
	v_exp_f32_e32 v229, v229
	v_add_f32_e32 v230, v221, v230
	s_waitcnt lgkmcnt(1)
	v_mfma_f32_32x32x16_bf16 v[80:95], v[242:245], v[130:133], v[80:95]
	v_exp_f32_e32 v213, v213
	v_add_f32_e32 v230, v222, v230
	v_add_f32_e32 v230, v215, v230
	v_add_f32_e32 v230, v228, v230
	v_add_f32_e32 v230, v229, v230
	v_add_f32_e32 v231, v213, v230
	v_mov_b32_e32 v241, v231
	s_waitcnt lgkmcnt(0)
	v_mfma_f32_32x32x16_bf16 v[64:79], v[246:249], v[130:133], v[64:79]
	ds_read_b128 v[242:245], v194 offset:32768
	ds_read_b128 v[246:249], v194 offset:40960
	v_cvt_pk_bf16_f32 v162, v162, v163
	v_cvt_pk_bf16_f32 v163, v164, v175
	v_cvt_pk_bf16_f32 v164, v176, v177
	v_cvt_pk_bf16_f32 v165, v165, v174
	v_cvt_pk_bf16_f32 v166, v166, v167
	v_cvt_pk_bf16_f32 v167, v172, v173
	s_waitcnt lgkmcnt(1)
	v_mfma_f32_32x32x16_bf16 v[80:95], v[242:245], v[118:121], v[80:95]
	v_cvt_pk_bf16_f32 v168, v168, v169
	v_cvt_pk_bf16_f32 v169, v170, v171
	v_cvt_pk_bf16_f32 v170, v223, v224
	v_cvt_pk_bf16_f32 v171, v225, v226
	v_cvt_pk_bf16_f32 v172, v227, v216
	v_cvt_pk_bf16_f32 v173, v217, v218
	v_cvt_pk_bf16_f32 v174, v219, v220
	s_waitcnt lgkmcnt(0)
	v_mfma_f32_32x32x16_bf16 v[64:79], v[246:249], v[118:121], v[64:79]
	ds_read_b128 v[242:245], v193 offset:32768
	ds_read_b128 v[246:249], v193 offset:40960
	v_cvt_pk_bf16_f32 v175, v221, v222
	v_cvt_pk_bf16_f32 v176, v215, v228
	v_cvt_pk_bf16_f32 v177, v229, v213
	v_permlane32_swap_b32_e32 v231, v241
	v_permlane32_swap_b32_e32 v162, v164
	s_waitcnt lgkmcnt(1)
	v_mfma_f32_32x32x16_bf16 v[80:95], v[242:245], v[114:117], v[80:95]
	v_permlane32_swap_b32_e32 v163, v165
	v_permlane32_swap_b32_e32 v166, v168
	v_permlane32_swap_b32_e32 v167, v169
	v_permlane32_swap_b32_e32 v170, v172
	s_waitcnt lgkmcnt(0)
	v_mfma_f32_32x32x16_bf16 v[64:79], v[246:249], v[114:117], v[64:79]
	ds_read_b128 v[242:245], v207 offset:32768
	ds_read_b128 v[246:249], v207 offset:40960
	v_permlane32_swap_b32_e32 v171, v173
	v_permlane32_swap_b32_e32 v174, v176
	v_permlane32_swap_b32_e32 v175, v177
	s_waitcnt lgkmcnt(1)
	v_mfma_f32_32x32x16_bf16 v[80:95], v[242:245], v[110:113], v[80:95]
	s_waitcnt lgkmcnt(0)
	v_mfma_f32_32x32x16_bf16 v[64:79], v[246:249], v[110:113], v[64:79]
	ds_read_b128 v[242:245], v206 offset:32768
	ds_read_b128 v[246:249], v206 offset:40960
	s_waitcnt lgkmcnt(1)
	v_mfma_f32_32x32x16_bf16 v[80:95], v[242:245], v[106:109], v[80:95]
	s_waitcnt lgkmcnt(0)
	v_mfma_f32_32x32x16_bf16 v[64:79], v[246:249], v[106:109], v[64:79]
	s_cmp_ge_u32 s40, s41
	s_cselect_b64 s[12:13], -1, 0
	s_and_b64 vcc, exec, s[12:13]
	s_cbranch_vccnz .LBB0_608
	v_add_co_u32_e32 v98, vcc, 0xffff8000, v182
	s_nop 1
	v_addc_co_u32_e32 v99, vcc, -1, v183, vcc
	global_load_dwordx4 v[98:101], v[98:99], off
	s_nop 0
	global_load_dwordx4 v[138:141], v[182:183], off
